# v11 with the hoisted LayerNorm context-row waits re-derived without relying on stores completing after older loads
# speedup vs baseline: 1.0068x; 1.0016x over previous
; DI unsigned pkh2(float lo, float hi) { return __builtin_bit_cast(unsigned, __builtin_amdgcn_cvt_pkrtz(lo, hi)); }
; DI float hlo(unsigned u) { return (float)__builtin_bit_cast(f16x2_t, u).x; }
; DI float hhi(unsigned u) { return (float)__builtin_bit_cast(f16x2_t, u).y; }
; DI void lnmod_phase(const Args& A, LAS unsigned char* lds, int tid, int bid, int G, bool init, int l_norm, int i_norm, int l_mod, int i_mod, bool want_dt, int nrows, bool ctx_partial, const float* gprev, const float* bprev) {
;     ...
;         for (int j = 0; j < 4; ++j) v[j] = init ? fn[j] : (f32x4){hlo(un[j].x), hhi(un[j].x), hlo(un[j].y), hhi(un[j].y)};
;         { const int rown = row + G * 8;
;           if (rown < nrows) {
;               if (init) { const float* xin = rown < M_LAT ? A.in[I_X] + (size_t)rown * DM : A.in[I_CTX] + (size_t)(rown - M_LAT) * DM;
; #pragma unroll
;                   for (int j = 0; j < 4; ++j) fn[j] = *(const f32x4*)(xin + 256 * j + 4 * lane); }
;               else {
; #pragma unroll
;                   for (int j = 0; j < 4; ++j) un[j] = *(const u32x2*)(X16 + (size_t)rown * DM + 256 * j + 4 * lane); } } }
;         f32x2* STAT = (f32x2*)(A.ws + WS_STAT);
;         if (ctx_partial && row >= M_LAT) {
;             { const f32x2 st = STAT[row];
; #pragma unroll
;               for (int j = 0; j < 4; ++j) v[j] = (v[j] - st.x) * st.y * *(const f32x4*)(gprev + 256 * j + 4 * lane) + *(const f32x4*)(bprev + 256 * j + 4 * lane); }
;             const float* t0 = (const float*)(A.ws + WS_T) + (size_t)(row - M_LAT) * DM; const float* t1 = t0 + (size_t)M_CTX * DM; const float* t2 = t1 + (size_t)M_CTX * DM; const float* t3 = t2 + (size_t)M_CTX * DM;
; #pragma unroll
;             for (int j = 0; j < 4; ++j) { v[j] = v[j] * ALPHA + (*(const f32x4*)(t0 + 256 * j + 4 * lane) + *(const f32x4*)(t1 + 256 * j + 4 * lane)) + (*(const f32x4*)(t2 + 256 * j + 4 * lane) + *(const f32x4*)(t3 + 256 * j + 4 * lane)); u32x2 w_; w_.x = pkh2(v[j].x, v[j].y); w_.y = pkh2(v[j].z, v[j].w); *(u32x2*)(xout + 256 * j + 4 * lane) = w_; }
.LBB0_207:
	s_or_b64 exec, exec, s[6:7]
	v_cvt_f32_f16_sdwa v106, v92 dst_sel:DWORD dst_unused:UNUSED_PAD src0_sel:WORD_1
	v_cvt_f32_f16_e32 v90, v92
	v_cvt_f32_f16_sdwa v91, v93 dst_sel:DWORD dst_unused:UNUSED_PAD src0_sel:WORD_1
	v_cvt_f32_f16_e32 v107, v93
	v_cvt_f32_f16_sdwa v102, v94 dst_sel:DWORD dst_unused:UNUSED_PAD src0_sel:WORD_1
	v_cvt_f32_f16_e32 v92, v94
	v_cvt_f32_f16_sdwa v93, v95 dst_sel:DWORD dst_unused:UNUSED_PAD src0_sel:WORD_1
	v_cvt_f32_f16_e32 v103, v95
	v_cvt_f32_f16_sdwa v97, v98 dst_sel:DWORD dst_unused:UNUSED_PAD src0_sel:WORD_1
	v_cvt_f32_f16_e32 v96, v98
	v_cvt_f32_f16_sdwa v95, v99 dst_sel:DWORD dst_unused:UNUSED_PAD src0_sel:WORD_1
	v_cvt_f32_f16_e32 v94, v99
	v_cvt_f32_f16_sdwa v104, v88 dst_sel:DWORD dst_unused:UNUSED_PAD src0_sel:WORD_1
	v_cvt_f32_f16_e32 v100, v88
	v_cvt_f32_f16_sdwa v108, v89 dst_sel:DWORD dst_unused:UNUSED_PAD src0_sel:WORD_1
	v_cvt_f32_f16_e32 v98, v89
	v_readlane_b32 s36, v253, 23
	s_movk_i32 s6, 0x7fff
	v_readlane_b32 s38, v253, 25
	v_readlane_b32 s39, v253, 26
	v_cmp_lt_i32_e32 vcc, s6, v86
	v_readlane_b32 s37, v253, 24
	v_lshl_add_u64 v[88:89], s[38:39], 0, v[64:65]
	s_and_saveexec_b64 s[6:7], vcc
	s_cbranch_execz .LBB0_209
	v_readlane_b32 s38, v253, 25
	v_readlane_b32 s39, v253, 26
	v_add_u32_e32 v146, 0xffff8000, v86
	s_nop 1
	v_lshl_add_u64 v[110:111], s[38:39], 0, v[74:75]
	global_load_dwordx2 v[122:123], v[110:111], off
	v_readlane_b32 s36, v251, 61
	v_readlane_b32 s37, v251, 62
	s_mov_b32 s19, 0x800000
	global_load_dwordx4 v[172:175], v[68:69], off
	global_load_dwordx4 v[118:121], v[70:71], off
	global_load_dwordx4 v[176:179], v[68:69], off offset:1024
	global_load_dwordx4 v[180:183], v[70:71], off offset:1024
	global_load_dwordx4 v[184:187], v[68:69], off offset:2048
	global_load_dwordx4 v[188:191], v[70:71], off offset:2048
	global_load_dwordx4 v[192:195], v[68:69], off offset:3072
	global_load_dwordx4 v[196:199], v[70:71], off offset:3072
	s_waitcnt vmcnt(8)
	v_sub_f32_e32 v111, v106, v122
	v_sub_f32_e32 v110, v90, v122
	v_sub_f32_e32 v90, v107, v122
	v_pk_mul_f32 v[106:107], v[122:123], v[110:111] op_sel:[1,0]
	v_sub_f32_e32 v91, v91, v122
	v_pk_mul_f32 v[90:91], v[122:123], v[90:91] op_sel:[1,0]
	v_sub_f32_e32 v93, v93, v122
	v_sub_f32_e32 v97, v97, v122
	v_sub_f32_e32 v96, v96, v122
	v_sub_f32_e32 v95, v95, v122
	v_sub_f32_e32 v94, v94, v122
	v_sub_f32_e32 v101, v104, v122
	v_sub_f32_e32 v100, v100, v122
	v_sub_f32_e32 v99, v108, v122
	v_sub_f32_e32 v98, v98, v122
	v_pk_mul_f32 v[108:109], v[122:123], v[100:101] op_sel:[1,0]
	s_waitcnt vmcnt(6)
	v_pk_fma_f32 v[126:127], v[172:173], v[106:107], v[118:119]
	v_pk_fma_f32 v[90:91], v[174:175], v[90:91], v[120:121]
	v_sub_f32_e32 v107, v102, v122
	v_sub_f32_e32 v106, v92, v122
	v_sub_f32_e32 v92, v103, v122
	v_pk_mul_f32 v[102:103], v[122:123], v[92:93] op_sel:[1,0]
	v_pk_mul_f32 v[92:93], v[122:123], v[106:107] op_sel:[1,0]
	v_pk_mul_f32 v[106:107], v[122:123], v[96:97] op_sel:[1,0]
	s_waitcnt vmcnt(4)
	v_pk_fma_f32 v[92:93], v[92:93], v[176:177], v[180:181]
	v_pk_fma_f32 v[176:177], v[102:103], v[178:179], v[182:183]
	v_pk_mul_f32 v[102:103], v[122:123], v[94:95] op_sel:[1,0]
	s_waitcnt vmcnt(2)
	v_pk_fma_f32 v[184:185], v[106:107], v[184:185], v[188:189]
	v_pk_fma_f32 v[186:187], v[102:103], v[186:187], v[190:191]
	v_pk_mul_f32 v[106:107], v[122:123], v[98:99] op_sel:[1,0]
	s_waitcnt vmcnt(0)
	v_pk_fma_f32 v[192:193], v[108:109], v[192:193], v[196:197]
	v_lshlrev_b64 v[102:103], 12, v[146:147]
	v_lshl_add_u64 v[102:103], s[36:37], 0, v[102:103]
	v_lshlrev_b32_e32 v146, 2, v66
	v_lshl_add_u64 v[108:109], v[102:103], 0, v[146:147]
	v_add_co_u32_e32 v172, vcc, s19, v108
	global_load_dwordx4 v[118:121], v[108:109], off
	s_nop 1
	v_addc_co_u32_e32 v173, vcc, 0, v109, vcc
	global_load_dwordx4 v[122:125], v[172:173], off
	s_mov_b64 s[36:37], 0x800000
	v_lshl_add_u64 v[112:113], v[108:109], 0, s[36:37]
	s_mov_b64 s[36:37], 0x1000000
	v_lshl_add_u64 v[174:175], v[108:109], 0, s[36:37]
	s_mov_b64 s[36:37], 0x1800000
	v_lshl_add_u64 v[180:181], v[108:109], 0, s[36:37]
	s_mov_b32 s19, 0x1000000
	v_add_co_u32_e32 v182, vcc, s19, v108
	s_mov_b32 s19, 0x1800000
	s_nop 1
	v_addc_co_u32_e32 v183, vcc, 0, v109, vcc
	global_load_dwordx4 v[188:191], v[182:183], off
	v_add_co_u32_e32 v200, vcc, s19, v108
	s_nop 1
	v_addc_co_u32_e32 v201, vcc, 0, v109, vcc
	global_load_dwordx4 v[202:205], v[200:201], off
	global_load_dwordx4 v[218:221], v[108:109], off offset:1024
	global_load_dwordx4 v[222:225], v[112:113], off offset:1024
	global_load_dwordx4 v[226:229], v[174:175], off offset:1024
	global_load_dwordx4 v[230:233], v[180:181], off offset:1024
	s_nop 0
	v_pk_fma_f32 v[194:195], v[106:107], v[194:195], v[198:199]
	s_mov_b32 s36, 0x3fd744fd
	s_waitcnt vmcnt(6)
; DI unsigned pkh2(float lo, float hi) { return __builtin_bit_cast(unsigned, __builtin_amdgcn_cvt_pkrtz(lo, hi)); }
; DI void lnmod_phase(const Args& A, LAS unsigned char* lds, int tid, int bid, int G, bool init, int l_norm, int i_norm, int l_mod, int i_mod, bool want_dt, int nrows, bool ctx_partial, const float* gprev, const float* bprev) {
;     ...
;         if (ctx_partial && row >= M_LAT) {
;             { const f32x2 st = STAT[row];
; #pragma unroll
;               for (int j = 0; j < 4; ++j) v[j] = (v[j] - st.x) * st.y * *(const f32x4*)(gprev + 256 * j + 4 * lane) + *(const f32x4*)(bprev + 256 * j + 4 * lane); }
;             const float* t0 = (const float*)(A.ws + WS_T) + (size_t)(row - M_LAT) * DM; const float* t1 = t0 + (size_t)M_CTX * DM; const float* t2 = t1 + (size_t)M_CTX * DM; const float* t3 = t2 + (size_t)M_CTX * DM;
; #pragma unroll
;             for (int j = 0; j < 4; ++j) { v[j] = v[j] * ALPHA + (*(const f32x4*)(t0 + 256 * j + 4 * lane) + *(const f32x4*)(t1 + 256 * j + 4 * lane)) + (*(const f32x4*)(t2 + 256 * j + 4 * lane) + *(const f32x4*)(t3 + 256 * j + 4 * lane)); u32x2 w_; w_.x = pkh2(v[j].x, v[j].y); w_.y = pkh2(v[j].z, v[j].w); *(u32x2*)(xout + 256 * j + 4 * lane) = w_; }
	v_pk_add_f32 v[172:173], v[120:121], v[124:125]
	s_nop 0
	v_pk_fma_f32 v[90:91], v[90:91], s[36:37], v[172:173] op_sel_hi:[1,0,1]
	s_nop 0
	v_pk_add_f32 v[114:115], v[118:119], v[122:123]
	v_pk_fma_f32 v[114:115], v[126:127], s[36:37], v[114:115] op_sel_hi:[1,0,1]
	s_nop 0
	s_mov_b32 s19, 0x21200000
	s_waitcnt vmcnt(4)
	v_pk_add_f32 v[200:201], v[190:191], v[204:205]
	v_pk_add_f32 v[188:189], v[188:189], v[202:203]
	v_pk_add_f32 v[200:201], v[90:91], v[200:201]
	v_pk_add_f32 v[90:91], v[114:115], v[188:189]
	v_add_co_u32_e32 v114, vcc, s19, v88
	v_cvt_pkrtz_f16_f32 v188, v90, v91
	v_cvt_pkrtz_f16_f32 v189, v200, v201
	v_addc_co_u32_e32 v115, vcc, 0, v89, vcc
	global_store_dwordx2 v[114:115], v[188:189], off
	s_nop 0
	s_waitcnt vmcnt(2)
	v_pk_add_f32 v[220:221], v[220:221], v[224:225]
	v_pk_add_f32 v[218:219], v[218:219], v[222:223]
	v_pk_fma_f32 v[176:177], v[176:177], s[36:37], v[220:221] op_sel_hi:[1,0,1]
	v_pk_fma_f32 v[92:93], v[92:93], s[36:37], v[218:219] op_sel_hi:[1,0,1]
	s_waitcnt vmcnt(0)
	v_pk_add_f32 v[228:229], v[228:229], v[232:233]
	v_pk_add_f32 v[226:227], v[226:227], v[230:231]
	v_pk_add_f32 v[126:127], v[176:177], v[228:229]
	v_pk_add_f32 v[92:93], v[92:93], v[226:227]
	v_cvt_pkrtz_f16_f32 v177, v126, v127
	v_cvt_pkrtz_f16_f32 v176, v92, v93
	global_store_dwordx2 v[114:115], v[176:177], off offset:512
	global_load_dwordx4 v[118:121], v[108:109], off offset:2048
	global_load_dwordx4 v[122:125], v[112:113], off offset:2048
	global_load_dwordx4 v[176:179], v[174:175], off offset:2048
	global_load_dwordx4 v[188:191], v[180:181], off offset:2048
	global_load_dwordx4 v[196:199], v[108:109], off offset:3072
	global_load_dwordx4 v[202:205], v[112:113], off offset:3072
	global_load_dwordx4 v[218:221], v[174:175], off offset:3072
	global_load_dwordx4 v[104:107], v[180:181], off offset:3072
	s_waitcnt vmcnt(6)
	v_pk_add_f32 v[110:111], v[120:121], v[124:125]
	v_pk_add_f32 v[118:119], v[118:119], v[122:123]
	v_pk_fma_f32 v[110:111], v[186:187], s[36:37], v[110:111] op_sel_hi:[1,0,1]
	v_pk_fma_f32 v[122:123], v[184:185], s[36:37], v[118:119] op_sel_hi:[1,0,1]
	s_waitcnt vmcnt(4)
	v_pk_add_f32 v[178:179], v[178:179], v[190:191]
	v_pk_add_f32 v[188:189], v[176:177], v[188:189]
	v_pk_add_f32 v[176:177], v[110:111], v[178:179]
	v_pk_add_f32 v[178:179], v[122:123], v[188:189]
	v_cvt_pkrtz_f16_f32 v111, v176, v177
	v_cvt_pkrtz_f16_f32 v110, v178, v179
	global_store_dwordx2 v[114:115], v[110:111], off offset:1024
	s_nop 0
	s_waitcnt vmcnt(2)
	v_pk_add_f32 v[198:199], v[198:199], v[204:205]
	v_pk_add_f32 v[196:197], v[196:197], v[202:203]
	v_pk_fma_f32 v[198:199], v[194:195], s[36:37], v[198:199] op_sel_hi:[1,0,1]
	v_pk_fma_f32 v[196:197], v[192:193], s[36:37], v[196:197] op_sel_hi:[1,0,1]
	s_nop 0
	s_waitcnt vmcnt(0)
	v_pk_add_f32 v[220:221], v[220:221], v[106:107]
	v_pk_add_f32 v[104:105], v[218:219], v[104:105]
	v_pk_add_f32 v[218:219], v[198:199], v[220:221]
	v_pk_add_f32 v[220:221], v[196:197], v[104:105]
	v_cvt_pkrtz_f16_f32 v105, v218, v219
	v_cvt_pkrtz_f16_f32 v104, v220, v221
	global_store_dwordx2 v[114:115], v[104:105], off offset:1536
	v_mov_b32_e32 v106, v91
	v_mov_b32_e32 v107, v200
	v_mov_b32_e32 v91, v201
	v_mov_b32_e32 v200, v93
	v_mov_b32_e32 v201, v126
	v_mov_b32_e32 v93, v127
	v_mov_b32_e32 v104, v221
	v_mov_b32_e32 v196, v219
	v_mov_b32_e32 v94, v176
	v_mov_b32_e32 v95, v177
	v_mov_b32_e32 v96, v178
	v_mov_b32_e32 v97, v179
	v_mov_b32_e32 v98, v218
	v_mov_b32_e32 v100, v220
	v_mov_b32_e32 v102, v200
	v_mov_b32_e32 v103, v201
	v_mov_b32_e32 v108, v196

; DI float hlo(unsigned u) { return (float)__builtin_bit_cast(f16x2_t, u).x; }
; DI float hhi(unsigned u) { return (float)__builtin_bit_cast(f16x2_t, u).y; }
; DI void lnmod_phase(const Args& A, LAS unsigned char* lds, int tid, int bid, int G, bool init, int l_norm, int i_norm, int l_mod, int i_mod, bool want_dt, int nrows, bool ctx_partial, const float* gprev, const float* bprev) {
;     ...
;         for (int j = 0; j < 4; ++j) v[j] = init ? fn[j] : (f32x4){hlo(un[j].x), hhi(un[j].x), hlo(un[j].y), hhi(un[j].y)};
;         { const int rown = row + G * 8;
;           if (rown < nrows) {
;               if (init) { const float* xin = rown < M_LAT ? A.in[I_X] + (size_t)rown * DM : A.in[I_CTX] + (size_t)(rown - M_LAT) * DM;
; #pragma unroll
;                   for (int j = 0; j < 4; ++j) fn[j] = *(const f32x4*)(xin + 256 * j + 4 * lane); }
;               else {
; #pragma unroll
;                   for (int j = 0; j < 4; ++j) un[j] = *(const u32x2*)(X16 + (size_t)rown * DM + 256 * j + 4 * lane); } } }
;         f32x2* STAT = (f32x2*)(A.ws + WS_STAT);
;         if (ctx_partial && row >= M_LAT) {
;             { const f32x2 st = STAT[row];
; #pragma unroll
;               for (int j = 0; j < 4; ++j) v[j] = (v[j] - st.x) * st.y * *(const f32x4*)(gprev + 256 * j + 4 * lane) + *(const f32x4*)(bprev + 256 * j + 4 * lane); }
.LBB0_231:
	s_or_b64 exec, exec, s[4:5]
	v_cvt_f32_f16_sdwa v108, v66 dst_sel:DWORD dst_unused:UNUSED_PAD src0_sel:WORD_1
	v_cvt_f32_f16_e32 v64, v66
	v_cvt_f32_f16_sdwa v65, v67 dst_sel:DWORD dst_unused:UNUSED_PAD src0_sel:WORD_1
	v_cvt_f32_f16_e32 v109, v67
	v_cvt_f32_f16_sdwa v66, v72 dst_sel:DWORD dst_unused:UNUSED_PAD src0_sel:WORD_1
	v_cvt_f32_f16_e32 v68, v72
	v_cvt_f32_f16_sdwa v69, v73 dst_sel:DWORD dst_unused:UNUSED_PAD src0_sel:WORD_1
	v_cvt_f32_f16_e32 v67, v73
	v_cvt_f32_f16_sdwa v73, v70 dst_sel:DWORD dst_unused:UNUSED_PAD src0_sel:WORD_1
	v_cvt_f32_f16_e32 v72, v70
	v_cvt_f32_f16_sdwa v75, v71 dst_sel:DWORD dst_unused:UNUSED_PAD src0_sel:WORD_1
	v_cvt_f32_f16_e32 v74, v71
	v_cvt_f32_f16_sdwa v70, v76 dst_sel:DWORD dst_unused:UNUSED_PAD src0_sel:WORD_1
	v_cvt_f32_f16_e32 v76, v76
	v_cvt_f32_f16_sdwa v106, v77 dst_sel:DWORD dst_unused:UNUSED_PAD src0_sel:WORD_1
	v_cvt_f32_f16_e32 v78, v77
	s_movk_i32 s4, 0x7fff
	v_cmp_lt_i32_e32 vcc, s4, v118
	v_readlane_b32 s4, v253, 37
	v_readlane_b32 s40, v253, 23
	v_readlane_b32 s5, v253, 38
	v_readlane_b32 s42, v253, 25
	v_readlane_b32 s43, v253, 26
	s_and_b64 s[36:37], s[4:5], vcc
	v_readlane_b32 s41, v253, 24
	v_lshl_add_u64 v[104:105], s[42:43], 0, v[82:83]
	s_and_saveexec_b64 s[4:5], s[36:37]
	s_cbranch_execz .LBB0_233
	v_readlane_b32 s38, v253, 25
	v_readlane_b32 s39, v253, 26
	v_add_u32_e32 v146, 0xffff8000, v118
	s_nop 1
	v_lshl_add_u64 v[110:111], s[38:39], 0, v[92:93]
	global_load_dwordx2 v[120:121], v[110:111], off
	v_readlane_b32 s36, v251, 61
	v_readlane_b32 s37, v251, 62
	s_mov_b32 s7, 0x800000
	global_load_dwordx4 v[130:133], v[86:87], off
	global_load_dwordx4 v[112:115], v[88:89], off
	global_load_dwordx4 v[134:137], v[86:87], off offset:1024
	global_load_dwordx4 v[138:141], v[88:89], off offset:1024
	global_load_dwordx4 v[154:157], v[86:87], off offset:2048
	global_load_dwordx4 v[160:163], v[88:89], off offset:2048
	global_load_dwordx4 v[164:167], v[86:87], off offset:3072
	global_load_dwordx4 v[168:171], v[88:89], off offset:3072
	s_waitcnt vmcnt(8)
	v_sub_f32_e32 v111, v108, v120
	v_sub_f32_e32 v110, v64, v120
	v_sub_f32_e32 v64, v109, v120
	v_pk_mul_f32 v[122:123], v[120:121], v[110:111] op_sel:[1,0]
	v_sub_f32_e32 v65, v65, v120
	v_pk_mul_f32 v[64:65], v[120:121], v[64:65] op_sel:[1,0]
	v_sub_f32_e32 v69, v69, v120
	s_waitcnt vmcnt(6)
	v_pk_fma_f32 v[114:115], v[132:133], v[64:65], v[114:115]
	v_sub_f32_e32 v65, v66, v120
	v_sub_f32_e32 v64, v68, v120
	v_sub_f32_e32 v68, v67, v120
	v_pk_fma_f32 v[128:129], v[130:131], v[122:123], v[112:113]
	v_pk_mul_f32 v[112:113], v[120:121], v[68:69] op_sel:[1,0]
	v_pk_mul_f32 v[68:69], v[120:121], v[64:65] op_sel:[1,0]
	s_waitcnt vmcnt(4)
	v_pk_fma_f32 v[68:69], v[68:69], v[134:135], v[138:139]
	v_pk_fma_f32 v[138:139], v[112:113], v[136:137], v[140:141]
	v_sub_f32_e32 v135, v73, v120
	v_sub_f32_e32 v134, v72, v120
	v_sub_f32_e32 v137, v75, v120
	v_sub_f32_e32 v136, v74, v120
	v_pk_mul_f32 v[140:141], v[120:121], v[136:137] op_sel:[1,0]
	v_pk_mul_f32 v[112:113], v[120:121], v[134:135] op_sel:[1,0]
	s_waitcnt vmcnt(2)
	v_pk_fma_f32 v[160:161], v[112:113], v[154:155], v[160:161]
	v_pk_fma_f32 v[162:163], v[140:141], v[156:157], v[162:163]
	v_sub_f32_e32 v154, v76, v120
	v_sub_f32_e32 v156, v78, v120
	v_sub_f32_e32 v155, v70, v120
	v_sub_f32_e32 v157, v106, v120
	v_pk_mul_f32 v[154:155], v[120:121], v[154:155] op_sel:[1,0]
	v_pk_mul_f32 v[70:71], v[120:121], v[156:157] op_sel:[1,0]
	s_waitcnt vmcnt(0)
; DI unsigned pkh2(float lo, float hi) { return __builtin_bit_cast(unsigned, __builtin_amdgcn_cvt_pkrtz(lo, hi)); }
; DI void lnmod_phase(const Args& A, LAS unsigned char* lds, int tid, int bid, int G, bool init, int l_norm, int i_norm, int l_mod, int i_mod, bool want_dt, int nrows, bool ctx_partial, const float* gprev, const float* bprev) {
;     ...
;             const float* t0 = (const float*)(A.ws + WS_T) + (size_t)(row - M_LAT) * DM; const float* t1 = t0 + (size_t)M_CTX * DM; const float* t2 = t1 + (size_t)M_CTX * DM; const float* t3 = t2 + (size_t)M_CTX * DM;
; #pragma unroll
;             for (int j = 0; j < 4; ++j) { v[j] = v[j] * ALPHA + (*(const f32x4*)(t0 + 256 * j + 4 * lane) + *(const f32x4*)(t1 + 256 * j + 4 * lane)) + (*(const f32x4*)(t2 + 256 * j + 4 * lane) + *(const f32x4*)(t3 + 256 * j + 4 * lane)); u32x2 w_; w_.x = pkh2(v[j].x, v[j].y); w_.y = pkh2(v[j].z, v[j].w); *(u32x2*)(xout + 256 * j + 4 * lane) = w_; }
	v_pk_fma_f32 v[156:157], v[154:155], v[164:165], v[168:169]
	v_lshlrev_b64 v[64:65], 12, v[146:147]
	v_lshl_add_u64 v[64:65], s[36:37], 0, v[64:65]
	v_lshlrev_b32_e32 v146, 2, v84
	v_lshl_add_u64 v[110:111], v[64:65], 0, v[146:147]
	v_add_co_u32_e32 v130, vcc, s7, v110
	global_load_dwordx4 v[120:123], v[110:111], off
	s_nop 1
	v_addc_co_u32_e32 v131, vcc, 0, v111, vcc
	global_load_dwordx4 v[124:127], v[130:131], off
	s_mov_b64 s[36:37], 0x800000
	v_lshl_add_u64 v[132:133], v[110:111], 0, s[36:37]
	s_mov_b64 s[36:37], 0x1000000
	v_lshl_add_u64 v[76:77], v[110:111], 0, s[36:37]
	s_mov_b64 s[36:37], 0x1800000
	v_lshl_add_u64 v[134:135], v[110:111], 0, s[36:37]
	s_mov_b32 s7, 0x1000000
	v_add_co_u32_e32 v136, vcc, s7, v110
	s_mov_b32 s7, 0x1800000
	s_nop 1
	v_addc_co_u32_e32 v137, vcc, 0, v111, vcc
	global_load_dwordx4 v[172:175], v[136:137], off
	v_add_co_u32_e32 v142, vcc, s7, v110
	s_nop 1
	v_addc_co_u32_e32 v143, vcc, 0, v111, vcc
	global_load_dwordx4 v[176:179], v[142:143], off
	global_load_dwordx4 v[180:183], v[110:111], off offset:1024
	global_load_dwordx4 v[184:187], v[132:133], off offset:1024
	global_load_dwordx4 v[188:191], v[76:77], off offset:1024
	global_load_dwordx4 v[192:195], v[134:135], off offset:1024
	global_load_dwordx4 v[196:199], v[110:111], off offset:2048
	global_load_dwordx4 v[200:203], v[132:133], off offset:2048
	global_load_dwordx4 v[204:207], v[76:77], off offset:2048
	global_load_dwordx4 v[218:221], v[134:135], off offset:2048
	global_load_dwordx4 v[222:225], v[110:111], off offset:3072
	global_load_dwordx4 v[226:229], v[132:133], off offset:3072
	global_load_dwordx4 v[230:233], v[76:77], off offset:3072
	global_load_dwordx4 v[234:237], v[134:135], off offset:3072
	s_nop 0
	v_pk_fma_f32 v[70:71], v[70:71], v[166:167], v[170:171]
	s_mov_b32 s36, 0x3fd744fd
	s_waitcnt vmcnt(14)
	v_pk_add_f32 v[130:131], v[122:123], v[126:127]
	v_pk_add_f32 v[106:107], v[120:121], v[124:125]
	v_pk_fma_f32 v[130:131], v[114:115], s[36:37], v[130:131] op_sel_hi:[1,0,1]
	v_pk_fma_f32 v[114:115], v[128:129], s[36:37], v[106:107] op_sel_hi:[1,0,1]
	s_nop 0
	s_mov_b32 s7, 0x21200000
	s_nop 0
	s_waitcnt vmcnt(12)
	v_pk_add_f32 v[142:143], v[174:175], v[178:179]
	v_pk_add_f32 v[172:173], v[172:173], v[176:177]
	v_pk_add_f32 v[142:143], v[130:131], v[142:143]
	v_pk_add_f32 v[130:131], v[114:115], v[172:173]
	v_add_co_u32_e32 v114, vcc, s7, v104
	v_cvt_pkrtz_f16_f32 v172, v130, v131
	v_cvt_pkrtz_f16_f32 v173, v142, v143
	v_addc_co_u32_e32 v115, vcc, 0, v105, vcc
	global_store_dwordx2 v[114:115], v[172:173], off
	s_nop 0
	s_waitcnt vmcnt(10)
	v_pk_add_f32 v[182:183], v[182:183], v[186:187]
	v_pk_add_f32 v[180:181], v[180:181], v[184:185]
	v_pk_fma_f32 v[138:139], v[138:139], s[36:37], v[182:183] op_sel_hi:[1,0,1]
	v_pk_fma_f32 v[68:69], v[68:69], s[36:37], v[180:181] op_sel_hi:[1,0,1]
	s_waitcnt vmcnt(8)
	v_pk_add_f32 v[190:191], v[190:191], v[194:195]
	v_pk_add_f32 v[188:189], v[188:189], v[192:193]
	v_pk_add_f32 v[128:129], v[138:139], v[190:191]
	v_pk_add_f32 v[68:69], v[68:69], v[188:189]
	v_cvt_pkrtz_f16_f32 v139, v128, v129
	v_cvt_pkrtz_f16_f32 v138, v68, v69
	global_store_dwordx2 v[114:115], v[138:139], off offset:512
	s_waitcnt vmcnt(6)
	v_pk_add_f32 v[138:139], v[198:199], v[202:203]
	v_pk_add_f32 v[196:197], v[196:197], v[200:201]
	v_pk_fma_f32 v[138:139], v[162:163], s[36:37], v[138:139] op_sel_hi:[1,0,1]
	v_pk_fma_f32 v[200:201], v[160:161], s[36:37], v[196:197] op_sel_hi:[1,0,1]
	s_waitcnt vmcnt(4)
	v_pk_add_f32 v[206:207], v[206:207], v[220:221]
	v_pk_add_f32 v[204:205], v[204:205], v[218:219]
	v_pk_add_f32 v[206:207], v[138:139], v[206:207]
	v_pk_add_f32 v[204:205], v[200:201], v[204:205]
	v_cvt_pkrtz_f16_f32 v139, v206, v207
	v_cvt_pkrtz_f16_f32 v138, v204, v205
	global_store_dwordx2 v[114:115], v[138:139], off offset:1024
	s_nop 0
	s_waitcnt vmcnt(2)
	v_pk_add_f32 v[224:225], v[224:225], v[228:229]
	v_pk_add_f32 v[222:223], v[222:223], v[226:227]
	v_pk_fma_f32 v[70:71], v[70:71], s[36:37], v[224:225] op_sel_hi:[1,0,1]
	v_pk_fma_f32 v[156:157], v[156:157], s[36:37], v[222:223] op_sel_hi:[1,0,1]
	s_nop 0
	s_waitcnt vmcnt(0)
	v_pk_add_f32 v[236:237], v[232:233], v[236:237]
	v_pk_add_f32 v[234:235], v[230:231], v[234:235]
	v_pk_add_f32 v[236:237], v[70:71], v[236:237]
	v_pk_add_f32 v[234:235], v[156:157], v[234:235]
	v_cvt_pkrtz_f16_f32 v157, v236, v237
	v_cvt_pkrtz_f16_f32 v156, v234, v235
	global_store_dwordx2 v[114:115], v[156:157], off offset:1536
	v_mov_b32_e32 v230, v131
	v_mov_b32_e32 v231, v142
	v_mov_b32_e32 v131, v143
	v_mov_b32_e32 v156, v69
	v_mov_b32_e32 v157, v128
	v_mov_b32_e32 v69, v129
	v_mov_b32_e32 v70, v235
	v_mov_b32_e32 v142, v237
	v_mov_b32_e32 v64, v130
	v_mov_b32_e32 v65, v131
	v_mov_b32_e32 v66, v156
	v_mov_b32_e32 v67, v157
	v_mov_b32_e32 v72, v204
	v_mov_b32_e32 v73, v205
	v_mov_b32_e32 v74, v206
	v_mov_b32_e32 v75, v207
	v_mov_b32_e32 v76, v234
	v_mov_b32_e32 v78, v236
	v_mov_b32_e32 v106, v142
	v_mov_b32_e32 v108, v230
	v_mov_b32_e32 v109, v231

; DI float hlo(unsigned u) { return (float)__builtin_bit_cast(f16x2_t, u).x; }
; DI float hhi(unsigned u) { return (float)__builtin_bit_cast(f16x2_t, u).y; }
; DI void lnmod_phase(const Args& A, LAS unsigned char* lds, int tid, int bid, int G, bool init, int l_norm, int i_norm, int l_mod, int i_mod, bool want_dt, int nrows, bool ctx_partial, const float* gprev, const float* bprev) {
;     ...
;         for (int j = 0; j < 4; ++j) v[j] = init ? fn[j] : (f32x4){hlo(un[j].x), hhi(un[j].x), hlo(un[j].y), hhi(un[j].y)};
;         { const int rown = row + G * 8;
;           if (rown < nrows) {
;               if (init) { const float* xin = rown < M_LAT ? A.in[I_X] + (size_t)rown * DM : A.in[I_CTX] + (size_t)(rown - M_LAT) * DM;
; #pragma unroll
;                   for (int j = 0; j < 4; ++j) fn[j] = *(const f32x4*)(xin + 256 * j + 4 * lane); }
;               else {
; #pragma unroll
;                   for (int j = 0; j < 4; ++j) un[j] = *(const u32x2*)(X16 + (size_t)rown * DM + 256 * j + 4 * lane); } } }
;         f32x2* STAT = (f32x2*)(A.ws + WS_STAT);
;         if (ctx_partial && row >= M_LAT) {
;             { const f32x2 st = STAT[row];
; #pragma unroll
;               for (int j = 0; j < 4; ++j) v[j] = (v[j] - st.x) * st.y * *(const f32x4*)(gprev + 256 * j + 4 * lane) + *(const f32x4*)(bprev + 256 * j + 4 * lane); }
.LBB0_282:
	s_or_b64 exec, exec, s[4:5]
	v_cvt_f32_f16_sdwa v104, v90 dst_sel:DWORD dst_unused:UNUSED_PAD src0_sel:WORD_1
	v_cvt_f32_f16_e32 v88, v90
	v_cvt_f32_f16_sdwa v89, v91 dst_sel:DWORD dst_unused:UNUSED_PAD src0_sel:WORD_1
	v_cvt_f32_f16_e32 v105, v91
	v_cvt_f32_f16_sdwa v100, v92 dst_sel:DWORD dst_unused:UNUSED_PAD src0_sel:WORD_1
	v_cvt_f32_f16_e32 v90, v92
	v_cvt_f32_f16_sdwa v91, v93 dst_sel:DWORD dst_unused:UNUSED_PAD src0_sel:WORD_1
	v_cvt_f32_f16_e32 v101, v93
	v_cvt_f32_f16_sdwa v95, v96 dst_sel:DWORD dst_unused:UNUSED_PAD src0_sel:WORD_1
	v_cvt_f32_f16_e32 v94, v96
	v_cvt_f32_f16_sdwa v93, v97 dst_sel:DWORD dst_unused:UNUSED_PAD src0_sel:WORD_1
	v_cvt_f32_f16_e32 v92, v97
	v_cvt_f32_f16_sdwa v102, v86 dst_sel:DWORD dst_unused:UNUSED_PAD src0_sel:WORD_1
	v_cvt_f32_f16_e32 v98, v86
	v_cvt_f32_f16_sdwa v106, v87 dst_sel:DWORD dst_unused:UNUSED_PAD src0_sel:WORD_1
	v_cvt_f32_f16_e32 v96, v87
	s_movk_i32 s4, 0x7fff
	v_cmp_lt_i32_e32 vcc, s4, v84
	v_readlane_b32 s4, v253, 37
	v_readlane_b32 s28, v253, 23
	v_readlane_b32 s5, v253, 38
	v_readlane_b32 s30, v253, 25
	v_readlane_b32 s31, v253, 26
	s_and_b64 s[24:25], s[4:5], vcc
	v_readlane_b32 s29, v253, 24
	v_lshl_add_u64 v[86:87], s[30:31], 0, v[64:65]
	s_and_saveexec_b64 s[4:5], s[24:25]
	s_cbranch_execz .LBB0_284
	v_readlane_b32 s26, v253, 25
	v_readlane_b32 s27, v253, 26
	v_add_u32_e32 v146, 0xffff8000, v84
	s_nop 1
	v_lshl_add_u64 v[108:109], s[26:27], 0, v[74:75]
	global_load_dwordx2 v[116:117], v[108:109], off
	v_readlane_b32 s24, v251, 61
	v_readlane_b32 s25, v251, 62
	s_mov_b32 s9, 0x800000
	global_load_dwordx4 v[124:127], v[68:69], off
	global_load_dwordx4 v[112:115], v[70:71], off
	global_load_dwordx4 v[128:131], v[68:69], off offset:1024
	global_load_dwordx4 v[132:135], v[70:71], off offset:1024
	global_load_dwordx4 v[136:139], v[68:69], off offset:2048
	global_load_dwordx4 v[140:143], v[70:71], off offset:2048
	global_load_dwordx4 v[154:157], v[68:69], off offset:3072
	global_load_dwordx4 v[160:163], v[70:71], off offset:3072
	s_waitcnt vmcnt(8)
	v_sub_f32_e32 v109, v104, v116
	v_sub_f32_e32 v108, v88, v116
	v_sub_f32_e32 v88, v105, v116
	v_pk_mul_f32 v[104:105], v[116:117], v[108:109] op_sel:[1,0]
	v_sub_f32_e32 v89, v89, v116
	v_pk_mul_f32 v[88:89], v[116:117], v[88:89] op_sel:[1,0]
	v_sub_f32_e32 v91, v91, v116
	v_sub_f32_e32 v95, v95, v116
	v_sub_f32_e32 v94, v94, v116
	v_sub_f32_e32 v93, v93, v116
	v_sub_f32_e32 v92, v92, v116
	v_sub_f32_e32 v99, v102, v116
	v_sub_f32_e32 v98, v98, v116
	v_sub_f32_e32 v97, v106, v116
	v_sub_f32_e32 v96, v96, v116
	v_pk_mul_f32 v[106:107], v[116:117], v[98:99] op_sel:[1,0]
	s_waitcnt vmcnt(6)
	v_pk_fma_f32 v[120:121], v[124:125], v[104:105], v[112:113]
	v_pk_fma_f32 v[88:89], v[126:127], v[88:89], v[114:115]
	v_sub_f32_e32 v105, v100, v116
	v_sub_f32_e32 v104, v90, v116
	v_sub_f32_e32 v90, v101, v116
	v_pk_mul_f32 v[100:101], v[116:117], v[90:91] op_sel:[1,0]
	v_pk_mul_f32 v[90:91], v[116:117], v[104:105] op_sel:[1,0]
	v_pk_mul_f32 v[104:105], v[116:117], v[94:95] op_sel:[1,0]
	s_waitcnt vmcnt(4)
	v_pk_fma_f32 v[90:91], v[90:91], v[128:129], v[132:133]
	v_pk_fma_f32 v[128:129], v[100:101], v[130:131], v[134:135]
	v_pk_mul_f32 v[100:101], v[116:117], v[92:93] op_sel:[1,0]
	s_waitcnt vmcnt(2)
	v_pk_fma_f32 v[136:137], v[104:105], v[136:137], v[140:141]
	v_pk_fma_f32 v[138:139], v[100:101], v[138:139], v[142:143]
	v_pk_mul_f32 v[104:105], v[116:117], v[96:97] op_sel:[1,0]
	s_waitcnt vmcnt(0)
; DI unsigned pkh2(float lo, float hi) { return __builtin_bit_cast(unsigned, __builtin_amdgcn_cvt_pkrtz(lo, hi)); }
; DI void lnmod_phase(const Args& A, LAS unsigned char* lds, int tid, int bid, int G, bool init, int l_norm, int i_norm, int l_mod, int i_mod, bool want_dt, int nrows, bool ctx_partial, const float* gprev, const float* bprev) {
;     ...
;             const float* t0 = (const float*)(A.ws + WS_T) + (size_t)(row - M_LAT) * DM; const float* t1 = t0 + (size_t)M_CTX * DM; const float* t2 = t1 + (size_t)M_CTX * DM; const float* t3 = t2 + (size_t)M_CTX * DM;
; #pragma unroll
;             for (int j = 0; j < 4; ++j) { v[j] = v[j] * ALPHA + (*(const f32x4*)(t0 + 256 * j + 4 * lane) + *(const f32x4*)(t1 + 256 * j + 4 * lane)) + (*(const f32x4*)(t2 + 256 * j + 4 * lane) + *(const f32x4*)(t3 + 256 * j + 4 * lane)); u32x2 w_; w_.x = pkh2(v[j].x, v[j].y); w_.y = pkh2(v[j].z, v[j].w); *(u32x2*)(xout + 256 * j + 4 * lane) = w_; }
	v_pk_fma_f32 v[154:155], v[106:107], v[154:155], v[160:161]
	v_lshlrev_b64 v[100:101], 12, v[146:147]
	v_lshl_add_u64 v[100:101], s[24:25], 0, v[100:101]
	v_lshlrev_b32_e32 v146, 2, v66
	v_lshl_add_u64 v[106:107], v[100:101], 0, v[146:147]
	v_add_co_u32_e32 v124, vcc, s9, v106
	global_load_dwordx4 v[112:115], v[106:107], off
	s_nop 1
	v_addc_co_u32_e32 v125, vcc, 0, v107, vcc
	global_load_dwordx4 v[116:119], v[124:125], off
	s_mov_b64 s[24:25], 0x800000
	v_lshl_add_u64 v[110:111], v[106:107], 0, s[24:25]
	s_mov_b64 s[24:25], 0x1000000
	v_lshl_add_u64 v[126:127], v[106:107], 0, s[24:25]
	s_mov_b64 s[24:25], 0x1800000
	v_lshl_add_u64 v[132:133], v[106:107], 0, s[24:25]
	s_mov_b32 s9, 0x1000000
	v_add_co_u32_e32 v134, vcc, s9, v106
	s_nop 1
	v_addc_co_u32_e32 v135, vcc, 0, v107, vcc
	s_mov_b32 s9, 0x1800000
	global_load_dwordx4 v[140:143], v[134:135], off
	v_add_co_u32_e32 v164, vcc, s9, v106
	s_nop 1
	v_addc_co_u32_e32 v165, vcc, 0, v107, vcc
	global_load_dwordx4 v[166:169], v[164:165], off
	global_load_dwordx4 v[170:173], v[106:107], off offset:1024
	global_load_dwordx4 v[174:177], v[110:111], off offset:1024
	global_load_dwordx4 v[178:181], v[126:127], off offset:1024
	global_load_dwordx4 v[182:185], v[132:133], off offset:1024
	global_load_dwordx4 v[186:189], v[106:107], off offset:2048
	global_load_dwordx4 v[190:193], v[110:111], off offset:2048
	global_load_dwordx4 v[194:197], v[126:127], off offset:2048
	global_load_dwordx4 v[198:201], v[132:133], off offset:2048
	global_load_dwordx4 v[202:205], v[106:107], off offset:3072
	global_load_dwordx4 v[218:221], v[110:111], off offset:3072
	global_load_dwordx4 v[222:225], v[126:127], off offset:3072
	global_load_dwordx4 v[226:229], v[132:133], off offset:3072
	s_nop 0
	v_pk_fma_f32 v[156:157], v[104:105], v[156:157], v[162:163]
	s_mov_b32 s24, 0x3fd744fd
	s_waitcnt vmcnt(14)
	v_pk_add_f32 v[124:125], v[114:115], v[118:119]
	s_nop 0
	v_pk_fma_f32 v[88:89], v[88:89], s[24:25], v[124:125] op_sel_hi:[1,0,1]
	v_pk_add_f32 v[112:113], v[112:113], v[116:117]
	s_nop 0
	v_pk_fma_f32 v[120:121], v[120:121], s[24:25], v[112:113] op_sel_hi:[1,0,1]
	s_mov_b32 s9, 0x21200000
	s_nop 0
	s_waitcnt vmcnt(12)
	v_pk_add_f32 v[164:165], v[142:143], v[168:169]
	v_pk_add_f32 v[140:141], v[140:141], v[166:167]
	v_pk_add_f32 v[164:165], v[88:89], v[164:165]
	v_pk_add_f32 v[88:89], v[120:121], v[140:141]
	v_add_co_u32_e32 v140, vcc, s9, v86
	v_cvt_pkrtz_f16_f32 v142, v88, v89
	v_cvt_pkrtz_f16_f32 v143, v164, v165
	v_addc_co_u32_e32 v141, vcc, 0, v87, vcc
	global_store_dwordx2 v[140:141], v[142:143], off
	s_nop 0
	s_waitcnt vmcnt(10)
	v_pk_add_f32 v[172:173], v[172:173], v[176:177]
	v_pk_add_f32 v[170:171], v[170:171], v[174:175]
	v_pk_fma_f32 v[128:129], v[128:129], s[24:25], v[172:173] op_sel_hi:[1,0,1]
	v_pk_fma_f32 v[90:91], v[90:91], s[24:25], v[170:171] op_sel_hi:[1,0,1]
	s_waitcnt vmcnt(8)
	v_pk_add_f32 v[180:181], v[180:181], v[184:185]
	v_pk_add_f32 v[178:179], v[178:179], v[182:183]
	v_pk_add_f32 v[122:123], v[128:129], v[180:181]
	v_pk_add_f32 v[90:91], v[90:91], v[178:179]
	v_cvt_pkrtz_f16_f32 v129, v122, v123
	v_cvt_pkrtz_f16_f32 v128, v90, v91
	global_store_dwordx2 v[140:141], v[128:129], off offset:512
	s_waitcnt vmcnt(6)
	v_pk_add_f32 v[128:129], v[188:189], v[192:193]
	v_pk_add_f32 v[186:187], v[186:187], v[190:191]
	v_pk_fma_f32 v[128:129], v[138:139], s[24:25], v[128:129] op_sel_hi:[1,0,1]
	v_pk_fma_f32 v[190:191], v[136:137], s[24:25], v[186:187] op_sel_hi:[1,0,1]
	s_waitcnt vmcnt(4)
	v_pk_add_f32 v[196:197], v[196:197], v[200:201]
	v_pk_add_f32 v[198:199], v[194:195], v[198:199]
	v_pk_add_f32 v[194:195], v[128:129], v[196:197]
	v_pk_add_f32 v[196:197], v[190:191], v[198:199]
	v_cvt_pkrtz_f16_f32 v129, v194, v195
	v_cvt_pkrtz_f16_f32 v128, v196, v197
	global_store_dwordx2 v[140:141], v[128:129], off offset:1024
	s_nop 0
	s_waitcnt vmcnt(2)
	v_pk_add_f32 v[204:205], v[204:205], v[220:221]
	v_pk_add_f32 v[202:203], v[202:203], v[218:219]
	v_pk_fma_f32 v[204:205], v[156:157], s[24:25], v[204:205] op_sel_hi:[1,0,1]
	v_pk_fma_f32 v[202:203], v[154:155], s[24:25], v[202:203] op_sel_hi:[1,0,1]
	s_nop 0
	s_waitcnt vmcnt(0)
	v_pk_add_f32 v[224:225], v[224:225], v[228:229]
	v_pk_add_f32 v[226:227], v[222:223], v[226:227]
	v_pk_add_f32 v[222:223], v[204:205], v[224:225]
	v_pk_add_f32 v[224:225], v[202:203], v[226:227]
	v_cvt_pkrtz_f16_f32 v227, v222, v223
	v_cvt_pkrtz_f16_f32 v226, v224, v225
	global_store_dwordx2 v[140:141], v[226:227], off offset:1536
	v_mov_b32_e32 v228, v89
	v_mov_b32_e32 v229, v164
	v_mov_b32_e32 v89, v165
	v_mov_b32_e32 v164, v91
	v_mov_b32_e32 v165, v122
	v_mov_b32_e32 v91, v123
	v_mov_b32_e32 v226, v225
	v_mov_b32_e32 v202, v223
	v_mov_b32_e32 v92, v194
	v_mov_b32_e32 v93, v195
	v_mov_b32_e32 v94, v196
	v_mov_b32_e32 v95, v197
	v_mov_b32_e32 v96, v222
	v_mov_b32_e32 v98, v224
	v_mov_b32_e32 v100, v164
	v_mov_b32_e32 v101, v165
	v_mov_b32_e32 v102, v226
	v_mov_b32_e32 v104, v228
	v_mov_b32_e32 v105, v229
	v_mov_b32_e32 v106, v202
